# attention phase: one static s_setprio 1 for the younger workgroup of each CU pair (blockIdx >= 256), reset at the phase end
# baseline (speedup 1.0000x reference)
; DEVI void attn_item(const P& p, int item, char* smem) {
;     const int tid = threadIdx.x, lane = tid & 63, w = tid >> 6, fr = lane & 15, fq = lane >> 4;
;     const int qt = item & 63, kvh = (item >> 6) & 3, b = item >> 8;
;     const int head = kvh * 4 + w, q0 = qt * 64;
;     const bf16_t* Q = (const bf16_t*)(p.ws + OFF_B) + ((size_t)(b * SEQ + q0)) * 1024 + head * 64;
;     const bf16_t* KB = (const bf16_t*)(p.ws + OFF_D);
;     const bf16_t* VT = (const bf16_t*)(p.ws + OFF_D + 17 * MiB);
;     char* sK = smem;
;     char* sV = smem + 8192;
;     const float sinkv = p.sink[head] * LOG2E;
;     const bf16_t* SGT = (const bf16_t*)(p.ws + OFF_C) + ((size_t)(b * SEQ + q0)) * 1024 + head * 64;
;     bf16_t* OG = (bf16_t*)(p.ws + OFF_A) + ((size_t)(b * SEQ + q0)) * 1024 + head * 64;
; #pragma unroll 1
;     for (int mh = 0; mh < 2; ++mh) {
;         const int mo = mh * 32;
;         bf16x8 Qf[2][2];
; #pragma unroll
;         for (int m = 0; m < 2; ++m)
; #pragma unroll
;             for (int kk = 0; kk < 2; ++kk) Qf[m][kk] = *(const bf16x8*)(Q + (size_t)(mo + 16 * m + fr) * 1024 + kk * 32 + fq * 8);
;         f32x4 O[4][2];
; #pragma unroll
;         for (int nd = 0; nd < 4; ++nd)
; #pragma unroll
;             for (int m = 0; m < 2; ++m) O[nd][m] = (f32x4){0.f, 0.f, 0.f, 0.f};
;         float mrow[2], lrow[2];
; #pragma unroll
;         for (int m = 0; m < 2; ++m) { mrow[m] = sinkv; lrow[m] = (fq == 0) ? 1.0f : 0.0f; }
; __global__ void __launch_bounds__(256, 2) fwd_megakernel(P p) {
;     ...
;     for (int it = bid; it < NB * 4 * 64; it += G) attn_item(p, it, smem);
.LBB0_1427:
	s_or_b64 exec, exec, s[2:3]
	s_cmpk_gt_i32 s86, 0x7ff
	s_barrier
	s_cbranch_scc1 .LBB0_1444
	v_xor_b32_e32 v4, v216, v172
	v_lshlrev_b32_e32 v4, 4, v4
	v_and_b32_e32 v4, 0x70, v4
	v_bfe_u32 v3, v172, 4, 2
	v_add_u32_e32 v123, 0, v4
	v_and_b32_e32 v4, 7, v172
	v_mov_b32_e32 v1, 0
	s_movk_i32 s2, 0x70
	v_and_b32_e32 v0, 0x70, v182
	v_and_b32_e32 v6, 14, v172
	v_bitop3_b32 v7, v175, v4, 3 bitop3:0x6c
	v_bitop3_b32 v4, v3, v4, 4 bitop3:0x36
	v_lshl_add_u64 v[98:99], s[54:55], 0, v[0:1]
	v_lshl_add_u64 v[100:101], s[0:1], 0, v[0:1]
	v_bitop3_b32 v0, v182, s2, v172 bitop3:0x48
	v_lshlrev_b32_e32 v125, 2, v3
	v_lshlrev_b32_e32 v8, 4, v4
	v_bitop3_b32 v4, v175, v6, 3 bitop3:0x6c
	v_add_u32_e32 v124, 0, v0
	v_sub_u32_e32 v0, v174, v125
	v_lshlrev_b32_e32 v9, 3, v4
	v_bitop3_b32 v4, v3, v6, 4 bitop3:0x36
	v_lshlrev_b32_e32 v2, 3, v3
	v_cmp_eq_u32_e32 vcc, 0, v3
	v_add_u32_e32 v126, 0x7f, v0
	v_lshrrev_b32_e32 v0, 2, v172
	v_lshlrev_b32_e32 v10, 3, v4
	v_bitop3_b32 v4, v3, v6, 8 bitop3:0x36
	v_bitop3_b32 v3, v3, v6, 12 bitop3:0x36
	v_lshl_add_u32 v5, v174, 7, 0
	v_and_b32_e32 v0, 8, v0
	v_add_u32_e32 v128, 32, v216
	v_lshlrev_b32_e32 v7, 4, v7
	v_lshlrev_b32_e32 v11, 3, v4
	v_lshlrev_b32_e32 v3, 3, v3
	v_and_b32_e32 v4, 16, v172
	s_mov_b32 s29, 0
	v_cndmask_b32_e64 v121, 0, 1.0, vcc
	v_lshlrev_b32_e32 v127, 7, v216
	v_lshlrev_b32_e32 v129, 7, v128
	s_lshl_b32 s34, s86, 6
	s_lshl_b32 s35, s27, 6
	v_lshlrev_b32_e32 v102, 1, v2
	v_mov_b32_e32 v103, v1
	v_lshlrev_b32_e32 v104, 1, v0
	v_mov_b32_e32 v105, v1
	s_movk_i32 s36, 0x2200
	v_lshlrev_b32_e32 v106, 1, v4
	v_mov_b32_e32 v107, v1
	v_add_u32_e32 v130, v5, v7
	v_add_u32_e32 v131, v5, v8
	s_movk_i32 s37, 0xfeff
	s_movk_i32 s38, 0x101
	s_movk_i32 s39, 0xfefe
	v_add_u32_e32 v132, v5, v9
	v_add_u32_e32 v133, v5, v10
	v_add_u32_e32 v134, v5, v11
	v_add_u32_e32 v135, v5, v3
	v_and_b32_e32 v2, 7, v172
	v_and_b32_e32 v3, 4, v2
	v_and_b32_e32 v4, 1, v2
	v_lshl_or_b32 v3, v4, 1, v3
	v_bfe_u32 v4, v216, 1, 3
	v_xor_b32_e32 v3, v3, v4
	v_bfe_u32 v4, v2, 1, 1
	v_lshlrev_b32_e32 v4, 3, v4
	v_lshl_or_b32 v124, v3, 4, v4
	v_xor_b32_e32 v228, 16, v124
	v_bfe_u32 v2, v172, 4, 2
	v_bfe_u32 v3, v174, 1, 3
	v_xor_b32_e32 v2, v2, v3
	v_lshl_add_u32 v132, v2, 4, v5
	v_xor_b32_e32 v134, 64, v132
	v_add_u32_e32 v133, v123, v127
	v_add_u32_e32 v135, v124, v127
	v_add_u32_e32 v217, v123, v129
	v_add_u32_e32 v229, v124, v129
	v_add_u32_e32 v214, v228, v127
	v_add_u32_e32 v215, v228, v129
	v_mov_b32_e32 v136, 0xf149f2ca
	s_mov_b32 s42, s86
	s_mov_b32 s99, 0
	s_cmpk_lt_u32 s86, 0x100
	s_cbranch_scc1 .Lat_noprio
	s_setprio 1
.Lat_noprio:
	s_branch .LBB0_1430
.LBB0_1429:
	s_add_i32 s42, s42, s27
	s_add_i32 s34, s34, s35
	s_cmpk_gt_i32 s42, 0x7ff
	s_cbranch_scc1 .LBB0_1444

; DEVI unsigned xb_ld(unsigned* p) { return __hip_atomic_load(p, __ATOMIC_RELAXED, __HIP_MEMORY_SCOPE_AGENT); }
; DEVI void xb_complete(XB& b) {
;     const unsigned G = gridDim.x;
;     unsigned sum, cnt, mine, sp = 0u;
;     for (;;) {
;         sum = 0u; cnt = 0u; mine = 0u;
; #pragma unroll
;         for (unsigned j = 0; j < 16; ++j) { const unsigned c = xb_ld(&b.bar[XB_XCNT(j)]); sum += c; cnt += (c > 0u) ? 1u : 0u; mine = (j == b.x) ? c : mine; }
;         if (sum == G) break;
;         __builtin_amdgcn_s_sleep(1);
;         if ((++sp & 255u) == 0u) { if (xb_ld(&b.bar[XB_TMO])) break; if (sp > XB_SPIN_CAP) { atomicAdd(&b.bar[XB_TMO], 1u); break; } }
;     }
;     b.nloc = mine > 0u ? mine : 1u; b.nx = cnt > 0u ? cnt : 1u;
; }
; DEVI void gsync(XB& b) {
;     asm volatile("s_waitcnt vmcnt(0)" ::: "memory");
;     __syncthreads();
;     if (threadIdx.x == 0) {
;         unsigned* bar = b.bar;
;         __builtin_amdgcn_s_waitcnt(0);
;         if (b.nloc == 0u) xb_complete(b);
.LBB0_1444:
	s_setprio 0
	s_waitcnt vmcnt(0)
	s_barrier
	s_mov_b64 s[0:1], exec
	v_readlane_b32 s2, v230, 17
	v_readlane_b32 s3, v230, 18
	v_readlane_b32 s52, v230, 25
	s_and_b64 s[2:3], s[0:1], s[2:3]
	v_readlane_b32 s53, v230, 26
	s_mov_b64 exec, s[2:3]
	s_cbranch_execz .LBB0_1497
	v_cmp_eq_u32_e32 vcc, 0, v178
	s_waitcnt vmcnt(0) expcnt(0) lgkmcnt(0)
	s_and_saveexec_b64 s[2:3], vcc
	s_cbranch_execz .LBB0_1460
	s_add_u32 s4, s90, 0x1ef48400
	s_addc_u32 s5, s91, 0
	s_add_u32 s6, s90, 0x1ef48500
	s_addc_u32 s7, s91, 0
	s_add_u32 s8, s90, 0x1ef48600
	s_addc_u32 s9, s91, 0
	s_add_u32 s10, s90, 0x1ef48700
	s_addc_u32 s11, s91, 0
	s_add_u32 s12, s90, 0x1ef48800
	s_addc_u32 s13, s91, 0
	s_add_u32 s14, s90, 0x1ef48900
	s_addc_u32 s15, s91, 0
	s_add_u32 s16, s90, 0x1ef48a00
	s_addc_u32 s17, s91, 0
	s_add_u32 s18, s90, 0x1ef48b00
	s_addc_u32 s19, s91, 0
	s_add_u32 s20, s90, 0x1ef48c00
	s_addc_u32 s21, s91, 0
	s_add_u32 s22, s90, 0x1ef48d00
	s_addc_u32 s23, s91, 0
	s_add_u32 s24, s90, 0x1ef48e00
	s_addc_u32 s25, s91, 0
	s_add_u32 s30, s90, 0x1ef48f00
	s_addc_u32 s31, s91, 0
	s_add_u32 s34, s90, 0x1ef49000
	s_addc_u32 s35, s91, 0
	s_add_u32 s36, s90, 0x1ef49100
	s_addc_u32 s37, s91, 0
	s_add_u32 s38, s90, 0x1ef49200
	s_addc_u32 s39, s91, 0
	s_add_u32 s42, s90, 0x1ef49300
	s_addc_u32 s43, s91, 0
	s_add_u32 s28, s90, 0x1ef48200
	s_addc_u32 s29, s91, 0
	s_mov_b32 s26, 1
	v_mov_b32_e32 v16, 0
	s_branch .LBB0_1448
